# early asynchronous L2 write-back from a helper wave at each XCD grid barrier entry
# baseline (speedup 1.0000x reference)
; #define LAS __attribute__((address_space(3)))
; DI unsigned xb_ld(unsigned* p)              { return __hip_atomic_load(p, __ATOMIC_RELAXED, __HIP_MEMORY_SCOPE_AGENT); }
; DI void xcd_barrier_complete(unsigned* bar, unsigned x, unsigned& nloc, unsigned& nx) {
;     const unsigned G = gridDim.x * gridDim.y * gridDim.z;
;     unsigned sum, cnt, mine, sp = 0u;
;     for (;;) {
;         sum = 0u; cnt = 0u; mine = 0u;
; #pragma unroll
;         for (unsigned j = 0; j < 16; ++j) { const unsigned c = xb_ld(&bar[XB_XCNT(j)]); sum += c; cnt += (c > 0u) ? 1u : 0u; mine = (j == x) ? c : mine; }
; DI void xcd_barrier(unsigned* bar, unsigned x, volatile LAS unsigned* st) {
;     asm volatile("s_waitcnt vmcnt(0)" ::: "memory");
;     __syncthreads();
;     if (threadIdx.x == 0) {
;         __builtin_amdgcn_s_waitcnt(0);
;         unsigned nloc = st[0], nx = st[1];
;         if (nloc == 0u) { xcd_barrier_complete(bar, x, nloc, nx); st[0] = nloc; st[1] = nx; }
.LBB0_216:
	s_waitcnt vmcnt(0)
	s_waitcnt vmcnt(0)
	s_barrier
	v_readfirstlane_b32 s101, v167
	s_cmp_eq_u32 s101, 64
	s_cbranch_scc0 .Lxb_nowb_1
	buffer_wbl2 sc1
.Lxb_nowb_1:
	s_and_saveexec_b64 s[0:1], s[92:93]
	s_xor_b64 s[2:3], exec, s[0:1]
	s_cbranch_execz .LBB0_269
	s_add_i32 s0, 0, 0x26be0
	v_mov_b32_e32 v0, s0
	s_waitcnt vmcnt(0) expcnt(0) lgkmcnt(0)
	ds_read_b32 v2, v0
	s_add_i32 s0, 0, 0x26be4
	v_mov_b32_e32 v0, s0
	ds_read_b32 v0, v0
	s_waitcnt lgkmcnt(1)
	v_cmp_ne_u32_e32 vcc, 0, v2
	s_cbranch_vccnz .LBB0_232
	s_add_u32 s4, s62, 0x31ba4200
	s_addc_u32 s5, s63, 0
	s_add_u32 s6, s62, 0x31ba4400
	s_addc_u32 s7, s63, 0
	s_add_u32 s16, s62, 0x31ba4500
	s_addc_u32 s17, s63, 0
	s_add_u32 s18, s62, 0x31ba4600
	s_addc_u32 s19, s63, 0
	s_add_u32 s20, s62, 0x31ba4700
	s_addc_u32 s21, s63, 0
	s_add_u32 s22, s62, 0x31ba4800
	s_addc_u32 s23, s63, 0
	s_add_u32 s24, s62, 0x31ba4900
	s_addc_u32 s25, s63, 0
	s_add_u32 s26, s62, 0x31ba4a00
	s_addc_u32 s27, s63, 0
	s_add_u32 s28, s62, 0x31ba4b00
	s_addc_u32 s29, s63, 0
	s_add_u32 s30, s62, 0x31ba4c00
	s_addc_u32 s31, s63, 0
	s_add_u32 s34, s62, 0x31ba4d00
	s_addc_u32 s35, s63, 0
	s_add_u32 s38, s62, 0x31ba4e00
	s_addc_u32 s39, s63, 0
	s_add_u32 s50, s62, 0x31ba4f00
	s_addc_u32 s51, s63, 0
	s_add_u32 s52, s62, 0x31ba5000
	s_addc_u32 s53, s63, 0
	s_add_u32 s54, s62, 0x31ba5100
	s_addc_u32 s55, s63, 0
	s_add_u32 s56, s62, 0x31ba5200
	s_addc_u32 s57, s63, 0
	s_mul_i32 s0, s65, s87
	s_add_u32 s66, s62, 0x31ba5300
	s_mul_i32 s0, s0, s64
	s_addc_u32 s67, s63, 0
	s_mov_b32 s1, 1
	v_mov_b32_e32 v16, 0
	s_branch .LBB0_220

; #define LAS __attribute__((address_space(3)))
; DI unsigned xb_ld(unsigned* p)              { return __hip_atomic_load(p, __ATOMIC_RELAXED, __HIP_MEMORY_SCOPE_AGENT); }
; DI void xcd_barrier_complete(unsigned* bar, unsigned x, unsigned& nloc, unsigned& nx) {
;     const unsigned G = gridDim.x * gridDim.y * gridDim.z;
;     unsigned sum, cnt, mine, sp = 0u;
;     for (;;) {
;         sum = 0u; cnt = 0u; mine = 0u;
; #pragma unroll
;         for (unsigned j = 0; j < 16; ++j) { const unsigned c = xb_ld(&bar[XB_XCNT(j)]); sum += c; cnt += (c > 0u) ? 1u : 0u; mine = (j == x) ? c : mine; }
; DI void xcd_barrier(unsigned* bar, unsigned x, volatile LAS unsigned* st) {
;     asm volatile("s_waitcnt vmcnt(0)" ::: "memory");
;     __syncthreads();
;     if (threadIdx.x == 0) {
;         __builtin_amdgcn_s_waitcnt(0);
;         unsigned nloc = st[0], nx = st[1];
;         if (nloc == 0u) { xcd_barrier_complete(bar, x, nloc, nx); st[0] = nloc; st[1] = nx; }
.LBB0_278:
	s_waitcnt vmcnt(0)
	s_barrier
	v_readfirstlane_b32 s101, v167
	s_cmp_eq_u32 s101, 64
	s_cbranch_scc0 .Lxb_nowb_2
	buffer_wbl2 sc1
.Lxb_nowb_2:
	s_and_saveexec_b64 s[2:3], s[92:93]
	s_cbranch_execz .LBB0_330
	s_add_i32 s0, 0, 0x26be0
	v_mov_b32_e32 v0, s0
	s_waitcnt vmcnt(0) expcnt(0) lgkmcnt(0)
	ds_read_b32 v2, v0
	s_add_i32 s0, 0, 0x26be4
	v_mov_b32_e32 v0, s0
	ds_read_b32 v0, v0
	s_waitcnt lgkmcnt(1)
	v_cmp_ne_u32_e32 vcc, 0, v2
	s_cbranch_vccnz .LBB0_294
	s_add_u32 s4, s62, 0x31ba4200
	s_addc_u32 s5, s63, 0
	s_add_u32 s6, s62, 0x31ba4400
	s_addc_u32 s7, s63, 0
	s_add_u32 s18, s62, 0x31ba4500
	s_addc_u32 s19, s63, 0
	s_add_u32 s20, s62, 0x31ba4600
	s_addc_u32 s21, s63, 0
	s_add_u32 s22, s62, 0x31ba4700
	s_addc_u32 s23, s63, 0
	s_add_u32 s24, s62, 0x31ba4800
	s_addc_u32 s25, s63, 0
	s_add_u32 s26, s62, 0x31ba4900
	s_addc_u32 s27, s63, 0
	s_add_u32 s28, s62, 0x31ba4a00
	s_addc_u32 s29, s63, 0
	s_add_u32 s30, s62, 0x31ba4b00
	s_addc_u32 s31, s63, 0
	s_add_u32 s34, s62, 0x31ba4c00
	s_addc_u32 s35, s63, 0
	s_add_u32 s38, s62, 0x31ba4d00
	s_addc_u32 s39, s63, 0
	s_add_u32 s50, s62, 0x31ba4e00
	s_addc_u32 s51, s63, 0
	s_add_u32 s52, s62, 0x31ba4f00
	s_addc_u32 s53, s63, 0
	s_add_u32 s54, s62, 0x31ba5000
	s_addc_u32 s55, s63, 0
	s_add_u32 s56, s62, 0x31ba5100
	s_addc_u32 s57, s63, 0
	s_add_u32 s66, s62, 0x31ba5200
	s_addc_u32 s67, s63, 0
	s_mul_i32 s0, s65, s87
	s_add_u32 s68, s62, 0x31ba5300
	s_mul_i32 s0, s0, s64
	s_addc_u32 s69, s63, 0
	s_mov_b32 s1, 1
	v_mov_b32_e32 v16, 0
	s_branch .LBB0_282

; #define LAS __attribute__((address_space(3)))
; DI unsigned xb_ld(unsigned* p)              { return __hip_atomic_load(p, __ATOMIC_RELAXED, __HIP_MEMORY_SCOPE_AGENT); }
; DI void xcd_barrier_complete(unsigned* bar, unsigned x, unsigned& nloc, unsigned& nx) {
;     const unsigned G = gridDim.x * gridDim.y * gridDim.z;
;     unsigned sum, cnt, mine, sp = 0u;
;     for (;;) {
;         sum = 0u; cnt = 0u; mine = 0u;
; #pragma unroll
;         for (unsigned j = 0; j < 16; ++j) { const unsigned c = xb_ld(&bar[XB_XCNT(j)]); sum += c; cnt += (c > 0u) ? 1u : 0u; mine = (j == x) ? c : mine; }
; DI void xcd_barrier(unsigned* bar, unsigned x, volatile LAS unsigned* st) {
;     asm volatile("s_waitcnt vmcnt(0)" ::: "memory");
;     __syncthreads();
;     if (threadIdx.x == 0) {
;         __builtin_amdgcn_s_waitcnt(0);
;         unsigned nloc = st[0], nx = st[1];
;         if (nloc == 0u) { xcd_barrier_complete(bar, x, nloc, nx); st[0] = nloc; st[1] = nx; }
.Lxb_nowb_3:
	s_and_saveexec_b64 s[2:3], s[92:93]
	s_cbranch_execz .LBB0_520
	s_add_i32 s0, 0, 0x26be0
	v_mov_b32_e32 v0, s0
	s_waitcnt vmcnt(0) expcnt(0) lgkmcnt(0)
	ds_read_b32 v2, v0
	s_add_i32 s0, 0, 0x26be4
	v_mov_b32_e32 v0, s0
	ds_read_b32 v0, v0
	s_waitcnt lgkmcnt(1)
	v_cmp_ne_u32_e32 vcc, 0, v2
	s_cbranch_vccnz .LBB0_484
	s_add_u32 s4, s62, 0x31ba4200
	s_addc_u32 s5, s63, 0
	s_add_u32 s6, s62, 0x31ba4400
	s_addc_u32 s7, s63, 0
	s_add_u32 s10, s62, 0x31ba4500
	s_addc_u32 s11, s63, 0
	s_add_u32 s14, s62, 0x31ba4600
	s_addc_u32 s15, s63, 0
	s_add_u32 s16, s62, 0x31ba4700
	s_addc_u32 s17, s63, 0
	s_add_u32 s18, s62, 0x31ba4800
	s_addc_u32 s19, s63, 0
	s_add_u32 s20, s62, 0x31ba4900
	s_addc_u32 s21, s63, 0
	s_add_u32 s22, s62, 0x31ba4a00
	s_addc_u32 s23, s63, 0
	s_add_u32 s24, s62, 0x31ba4b00
	s_addc_u32 s25, s63, 0
	s_add_u32 s26, s62, 0x31ba4c00
	s_addc_u32 s27, s63, 0
	s_add_u32 s28, s62, 0x31ba4d00
	s_addc_u32 s29, s63, 0
	s_add_u32 s30, s62, 0x31ba4e00
	s_addc_u32 s31, s63, 0
	s_add_u32 s34, s62, 0x31ba4f00
	s_addc_u32 s35, s63, 0
	s_add_u32 s54, s62, 0x31ba5000
	s_addc_u32 s55, s63, 0
	s_add_u32 s56, s62, 0x31ba5100
	s_addc_u32 s57, s63, 0
	s_add_u32 s66, s62, 0x31ba5200
	s_addc_u32 s67, s63, 0
	s_mul_i32 s0, s65, s87
	s_add_u32 s68, s62, 0x31ba5300
	s_mul_i32 s0, s0, s64
	s_addc_u32 s69, s63, 0
	s_mov_b32 s1, 1
	v_mov_b32_e32 v16, 0
	s_branch .LBB0_472

; #define LAS __attribute__((address_space(3)))
; DI unsigned xb_ld(unsigned* p)              { return __hip_atomic_load(p, __ATOMIC_RELAXED, __HIP_MEMORY_SCOPE_AGENT); }
; DI void xcd_barrier_complete(unsigned* bar, unsigned x, unsigned& nloc, unsigned& nx) {
;     const unsigned G = gridDim.x * gridDim.y * gridDim.z;
;     unsigned sum, cnt, mine, sp = 0u;
;     for (;;) {
;         sum = 0u; cnt = 0u; mine = 0u;
; #pragma unroll
;         for (unsigned j = 0; j < 16; ++j) { const unsigned c = xb_ld(&bar[XB_XCNT(j)]); sum += c; cnt += (c > 0u) ? 1u : 0u; mine = (j == x) ? c : mine; }
; DI void xcd_barrier(unsigned* bar, unsigned x, volatile LAS unsigned* st) {
;     asm volatile("s_waitcnt vmcnt(0)" ::: "memory");
;     __syncthreads();
;     if (threadIdx.x == 0) {
;         __builtin_amdgcn_s_waitcnt(0);
;         unsigned nloc = st[0], nx = st[1];
;         if (nloc == 0u) { xcd_barrier_complete(bar, x, nloc, nx); st[0] = nloc; st[1] = nx; }
.LBB0_636:
	s_waitcnt vmcnt(0)
	v_writelane_b32 v234, s88, 11
	s_waitcnt vmcnt(0)
	s_barrier
	v_readfirstlane_b32 s101, v167
	s_cmp_eq_u32 s101, 64
	s_cbranch_scc0 .Lxb_nowb_4
	buffer_wbl2 sc1
.Lxb_nowb_4:
	v_writelane_b32 v234, s89, 12
	s_and_saveexec_b64 s[2:3], s[92:93]
	s_cbranch_execz .LBB0_688
	s_add_i32 s0, 0, 0x26be0
	v_mov_b32_e32 v0, s0
	s_waitcnt vmcnt(0) expcnt(0) lgkmcnt(0)
	ds_read_b32 v2, v0
	s_add_i32 s0, 0, 0x26be4
	v_mov_b32_e32 v0, s0
	ds_read_b32 v0, v0
	s_waitcnt lgkmcnt(1)
	v_cmp_ne_u32_e32 vcc, 0, v2
	s_cbranch_vccnz .LBB0_652
	s_add_u32 s4, s62, 0x31ba4200
	s_addc_u32 s5, s63, 0
	s_add_u32 s6, s62, 0x31ba4400
	s_addc_u32 s7, s63, 0
	s_add_u32 s8, s62, 0x31ba4500
	s_addc_u32 s9, s63, 0
	s_add_u32 s10, s62, 0x31ba4600
	s_addc_u32 s11, s63, 0
	s_add_u32 s14, s62, 0x31ba4700
	s_addc_u32 s15, s63, 0
	s_add_u32 s16, s62, 0x31ba4800
	s_addc_u32 s17, s63, 0
	s_add_u32 s18, s62, 0x31ba4900
	s_addc_u32 s19, s63, 0
	s_add_u32 s20, s62, 0x31ba4a00
	s_addc_u32 s21, s63, 0
	s_add_u32 s22, s62, 0x31ba4b00
	s_addc_u32 s23, s63, 0
	s_add_u32 s24, s62, 0x31ba4c00
	s_addc_u32 s25, s63, 0
	s_add_u32 s26, s62, 0x31ba4d00
	s_addc_u32 s27, s63, 0
	s_add_u32 s28, s62, 0x31ba4e00
	s_addc_u32 s29, s63, 0
	s_add_u32 s30, s62, 0x31ba4f00
	s_addc_u32 s31, s63, 0
	s_add_u32 s34, s62, 0x31ba5000
	s_addc_u32 s35, s63, 0
	s_add_u32 s36, s62, 0x31ba5100
	s_addc_u32 s37, s63, 0
	s_add_u32 s38, s62, 0x31ba5200
	s_addc_u32 s39, s63, 0
	s_mul_i32 s0, s65, s87
	s_add_u32 s50, s62, 0x31ba5300
	s_mul_i32 s0, s0, s64
	s_addc_u32 s51, s63, 0
	s_mov_b32 s1, 1
	v_mov_b32_e32 v16, 0
	s_branch .LBB0_640

; #define LAS __attribute__((address_space(3)))
; DI unsigned xb_ld(unsigned* p)              { return __hip_atomic_load(p, __ATOMIC_RELAXED, __HIP_MEMORY_SCOPE_AGENT); }
; DI void xcd_barrier_complete(unsigned* bar, unsigned x, unsigned& nloc, unsigned& nx) {
;     const unsigned G = gridDim.x * gridDim.y * gridDim.z;
;     unsigned sum, cnt, mine, sp = 0u;
;     for (;;) {
;         sum = 0u; cnt = 0u; mine = 0u;
; #pragma unroll
;         for (unsigned j = 0; j < 16; ++j) { const unsigned c = xb_ld(&bar[XB_XCNT(j)]); sum += c; cnt += (c > 0u) ? 1u : 0u; mine = (j == x) ? c : mine; }
; DI void xcd_barrier(unsigned* bar, unsigned x, volatile LAS unsigned* st) {
;     asm volatile("s_waitcnt vmcnt(0)" ::: "memory");
;     __syncthreads();
;     if (threadIdx.x == 0) {
;         __builtin_amdgcn_s_waitcnt(0);
;         unsigned nloc = st[0], nx = st[1];
;         if (nloc == 0u) { xcd_barrier_complete(bar, x, nloc, nx); st[0] = nloc; st[1] = nx; }
.LBB0_865:
	s_waitcnt vmcnt(0)
	v_readlane_b32 s70, v234, 19
	v_readlane_b32 s71, v234, 20
	s_barrier
	v_readfirstlane_b32 s101, v167
	s_cmp_eq_u32 s101, 64
	s_cbranch_scc0 .Lxb_nowb_5
	buffer_wbl2 sc1
.Lxb_nowb_5:
	s_and_saveexec_b64 s[2:3], s[70:71]
	v_readlane_b32 s58, v234, 11
	v_readlane_b32 s59, v234, 12
	v_readlane_b32 s66, v234, 22
	v_readlane_b32 s74, v234, 15
	v_readlane_b32 s76, v234, 8
	s_mov_b32 s59, s47
	v_readlane_b32 s67, v234, 23
	v_readlane_b32 s68, v234, 21
	v_readlane_b32 s69, v234, 18
	v_readlane_b32 s72, v234, 17
	v_readlane_b32 s75, v234, 16
	v_readlane_b32 s77, v234, 9
	s_cbranch_execz .LBB0_917
	s_add_i32 s0, 0, 0x26be0
	v_mov_b32_e32 v0, s0
	s_waitcnt vmcnt(0) expcnt(0) lgkmcnt(0)
	ds_read_b32 v2, v0
	s_add_i32 s0, 0, 0x26be4
	v_mov_b32_e32 v0, s0
	ds_read_b32 v0, v0
	s_waitcnt lgkmcnt(1)
	v_cmp_ne_u32_e32 vcc, 0, v2
	s_cbranch_vccnz .LBB0_881
	s_add_u32 s4, s62, 0x31ba4200
	s_addc_u32 s5, s63, 0
	s_add_u32 s6, s62, 0x31ba4400
	s_addc_u32 s7, s63, 0
	s_add_u32 s8, s62, 0x31ba4500
	s_addc_u32 s9, s63, 0
	s_add_u32 s10, s62, 0x31ba4600
	s_addc_u32 s11, s63, 0
	s_add_u32 s14, s62, 0x31ba4700
	s_addc_u32 s15, s63, 0
	s_add_u32 s16, s62, 0x31ba4800
	s_addc_u32 s17, s63, 0
	s_add_u32 s18, s62, 0x31ba4900
	s_addc_u32 s19, s63, 0
	s_add_u32 s20, s62, 0x31ba4a00
	s_addc_u32 s21, s63, 0
	s_add_u32 s22, s62, 0x31ba4b00
	s_addc_u32 s23, s63, 0
	s_add_u32 s24, s62, 0x31ba4c00
	s_addc_u32 s25, s63, 0
	s_add_u32 s26, s62, 0x31ba4d00
	s_addc_u32 s27, s63, 0
	s_add_u32 s28, s62, 0x31ba4e00
	s_addc_u32 s29, s63, 0
	s_add_u32 s30, s62, 0x31ba4f00
	s_addc_u32 s31, s63, 0
	s_add_u32 s34, s62, 0x31ba5000
	s_addc_u32 s35, s63, 0
	s_add_u32 s36, s62, 0x31ba5100
	s_addc_u32 s37, s63, 0
	s_add_u32 s38, s62, 0x31ba5200
	s_addc_u32 s39, s63, 0
	s_mul_i32 s0, s65, s59
	s_add_u32 s50, s62, 0x31ba5300
	s_mul_i32 s0, s0, s64
	s_addc_u32 s51, s63, 0
	s_mov_b32 s1, 1
	v_mov_b32_e32 v16, 0
	s_branch .LBB0_869

; #define LAS __attribute__((address_space(3)))
; DI unsigned xb_ld(unsigned* p)              { return __hip_atomic_load(p, __ATOMIC_RELAXED, __HIP_MEMORY_SCOPE_AGENT); }
; DI void xcd_barrier_complete(unsigned* bar, unsigned x, unsigned& nloc, unsigned& nx) {
;     const unsigned G = gridDim.x * gridDim.y * gridDim.z;
;     unsigned sum, cnt, mine, sp = 0u;
;     for (;;) {
;         sum = 0u; cnt = 0u; mine = 0u;
; #pragma unroll
;         for (unsigned j = 0; j < 16; ++j) { const unsigned c = xb_ld(&bar[XB_XCNT(j)]); sum += c; cnt += (c > 0u) ? 1u : 0u; mine = (j == x) ? c : mine; }
; DI void xcd_barrier(unsigned* bar, unsigned x, volatile LAS unsigned* st) {
;     asm volatile("s_waitcnt vmcnt(0)" ::: "memory");
;     __syncthreads();
;     if (threadIdx.x == 0) {
;         __builtin_amdgcn_s_waitcnt(0);
;         unsigned nloc = st[0], nx = st[1];
;         if (nloc == 0u) { xcd_barrier_complete(bar, x, nloc, nx); st[0] = nloc; st[1] = nx; }
.LBB0_959:
	s_waitcnt vmcnt(0)
	s_waitcnt lgkmcnt(0)
	s_barrier
	v_readfirstlane_b32 s101, v167
	s_cmp_eq_u32 s101, 64
	s_cbranch_scc0 .Lxb_nowb_6
	buffer_wbl2 sc1
.Lxb_nowb_6:
	s_and_saveexec_b64 s[4:5], s[70:71]
	s_cbranch_execz .LBB0_1011
	s_add_i32 s0, 0, 0x26be0
	v_mov_b32_e32 v0, s0
	s_waitcnt vmcnt(0) expcnt(0) lgkmcnt(0)
	ds_read_b32 v2, v0
	s_add_i32 s0, 0, 0x26be4
	v_mov_b32_e32 v0, s0
	ds_read_b32 v0, v0
	s_waitcnt lgkmcnt(1)
	v_cmp_ne_u32_e32 vcc, 0, v2
	s_cbranch_vccnz .LBB0_975
	s_add_u32 s6, s62, 0x31ba4200
	s_addc_u32 s7, s63, 0
	s_add_u32 s8, s62, 0x31ba4400
	s_addc_u32 s9, s63, 0
	s_add_u32 s10, s62, 0x31ba4500
	s_addc_u32 s11, s63, 0
	s_add_u32 s14, s62, 0x31ba4600
	s_addc_u32 s15, s63, 0
	s_add_u32 s16, s62, 0x31ba4700
	s_addc_u32 s17, s63, 0
	s_add_u32 s18, s62, 0x31ba4800
	s_addc_u32 s19, s63, 0
	s_add_u32 s20, s62, 0x31ba4900
	s_addc_u32 s21, s63, 0
	s_add_u32 s22, s62, 0x31ba4a00
	s_addc_u32 s23, s63, 0
	s_add_u32 s24, s62, 0x31ba4b00
	s_addc_u32 s25, s63, 0
	s_add_u32 s26, s62, 0x31ba4c00
	s_addc_u32 s27, s63, 0
	s_add_u32 s28, s62, 0x31ba4d00
	s_addc_u32 s29, s63, 0
	s_add_u32 s30, s62, 0x31ba4e00
	s_addc_u32 s31, s63, 0
	s_add_u32 s34, s62, 0x31ba4f00
	s_addc_u32 s35, s63, 0
	s_add_u32 s36, s62, 0x31ba5000
	s_addc_u32 s37, s63, 0
	s_add_u32 s38, s62, 0x31ba5100
	s_addc_u32 s39, s63, 0
	s_add_u32 s48, s62, 0x31ba5200
	s_addc_u32 s49, s63, 0
	s_mul_i32 s0, s65, s59
	s_add_u32 s50, s62, 0x31ba5300
	s_mul_i32 s0, s0, s64
	s_addc_u32 s51, s63, 0
	s_mov_b32 s1, 1
	v_mov_b32_e32 v16, 0
	s_branch .LBB0_963

; #define LAS __attribute__((address_space(3)))
; DI unsigned xb_ld(unsigned* p)              { return __hip_atomic_load(p, __ATOMIC_RELAXED, __HIP_MEMORY_SCOPE_AGENT); }
; DI void xcd_barrier_complete(unsigned* bar, unsigned x, unsigned& nloc, unsigned& nx) {
;     const unsigned G = gridDim.x * gridDim.y * gridDim.z;
;     unsigned sum, cnt, mine, sp = 0u;
;     for (;;) {
;         sum = 0u; cnt = 0u; mine = 0u;
; #pragma unroll
;         for (unsigned j = 0; j < 16; ++j) { const unsigned c = xb_ld(&bar[XB_XCNT(j)]); sum += c; cnt += (c > 0u) ? 1u : 0u; mine = (j == x) ? c : mine; }
; DI void xcd_barrier(unsigned* bar, unsigned x, volatile LAS unsigned* st) {
;     asm volatile("s_waitcnt vmcnt(0)" ::: "memory");
;     __syncthreads();
;     if (threadIdx.x == 0) {
;         __builtin_amdgcn_s_waitcnt(0);
;         unsigned nloc = st[0], nx = st[1];
;         if (nloc == 0u) { xcd_barrier_complete(bar, x, nloc, nx); st[0] = nloc; st[1] = nx; }
.Lxb_nowb_7:
	s_and_saveexec_b64 s[0:1], s[70:71]
	s_xor_b64 s[4:5], exec, s[0:1]
	s_cbranch_execz .LBB0_1080
	s_add_i32 s0, 0, 0x26be0
	v_mov_b32_e32 v0, s0
	s_waitcnt vmcnt(0) expcnt(0) lgkmcnt(0)
	ds_read_b32 v2, v0
	s_add_i32 s0, 0, 0x26be4
	v_mov_b32_e32 v0, s0
	ds_read_b32 v0, v0
	s_waitcnt lgkmcnt(1)
	v_cmp_ne_u32_e32 vcc, 0, v2
	s_cbranch_vccnz .LBB0_1043
	s_add_u32 s6, s62, 0x31ba4200
	s_addc_u32 s7, s63, 0
	s_add_u32 s8, s62, 0x31ba4400
	s_addc_u32 s9, s63, 0
	s_add_u32 s10, s62, 0x31ba4500
	s_addc_u32 s11, s63, 0
	s_add_u32 s14, s62, 0x31ba4600
	s_addc_u32 s15, s63, 0
	s_add_u32 s16, s62, 0x31ba4700
	s_addc_u32 s17, s63, 0
	s_add_u32 s18, s62, 0x31ba4800
	s_addc_u32 s19, s63, 0
	s_add_u32 s20, s62, 0x31ba4900
	s_addc_u32 s21, s63, 0
	s_add_u32 s22, s62, 0x31ba4a00
	s_addc_u32 s23, s63, 0
	s_add_u32 s24, s62, 0x31ba4b00
	s_addc_u32 s25, s63, 0
	s_add_u32 s26, s62, 0x31ba4c00
	s_addc_u32 s27, s63, 0
	s_add_u32 s28, s62, 0x31ba4d00
	s_addc_u32 s29, s63, 0
	s_add_u32 s30, s62, 0x31ba4e00
	s_addc_u32 s31, s63, 0
	s_add_u32 s34, s62, 0x31ba4f00
	s_addc_u32 s35, s63, 0
	s_add_u32 s36, s62, 0x31ba5000
	s_addc_u32 s37, s63, 0
	s_add_u32 s38, s62, 0x31ba5100
	s_addc_u32 s39, s63, 0
	s_add_u32 s46, s62, 0x31ba5200
	s_addc_u32 s47, s63, 0
	s_mul_i32 s0, s65, s59
	s_add_u32 s48, s62, 0x31ba5300
	s_mul_i32 s0, s0, s64
	s_addc_u32 s49, s63, 0
	s_mov_b32 s1, 1
	v_mov_b32_e32 v16, 0
	s_branch .LBB0_1031

; #define LAS __attribute__((address_space(3)))
; DI unsigned xb_ld(unsigned* p)              { return __hip_atomic_load(p, __ATOMIC_RELAXED, __HIP_MEMORY_SCOPE_AGENT); }
; DI void xcd_barrier_complete(unsigned* bar, unsigned x, unsigned& nloc, unsigned& nx) {
;     const unsigned G = gridDim.x * gridDim.y * gridDim.z;
;     unsigned sum, cnt, mine, sp = 0u;
;     for (;;) {
;         sum = 0u; cnt = 0u; mine = 0u;
; #pragma unroll
;         for (unsigned j = 0; j < 16; ++j) { const unsigned c = xb_ld(&bar[XB_XCNT(j)]); sum += c; cnt += (c > 0u) ? 1u : 0u; mine = (j == x) ? c : mine; }
; DI void xcd_barrier(unsigned* bar, unsigned x, volatile LAS unsigned* st) {
;     asm volatile("s_waitcnt vmcnt(0)" ::: "memory");
;     __syncthreads();
;     if (threadIdx.x == 0) {
;         __builtin_amdgcn_s_waitcnt(0);
;         unsigned nloc = st[0], nx = st[1];
;         if (nloc == 0u) { xcd_barrier_complete(bar, x, nloc, nx); st[0] = nloc; st[1] = nx; }
.Lxb_nowb_8:
	s_and_saveexec_b64 s[2:3], s[70:71]
	s_cbranch_execz .LBB0_1160
	s_add_i32 s0, 0, 0x26be0
	v_mov_b32_e32 v0, s0
	s_waitcnt vmcnt(0) expcnt(0) lgkmcnt(0)
	ds_read_b32 v2, v0
	s_add_i32 s0, 0, 0x26be4
	v_mov_b32_e32 v0, s0
	ds_read_b32 v0, v0
	s_waitcnt lgkmcnt(1)
	v_cmp_ne_u32_e32 vcc, 0, v2
	s_cbranch_vccnz .LBB0_1124
	s_add_u32 s0, s62, 0x31ba4200
	s_addc_u32 s1, s63, 0
	s_add_u32 s4, s62, 0x31ba4400
	s_addc_u32 s5, s63, 0
	s_add_u32 s6, s62, 0x31ba4500
	s_addc_u32 s7, s63, 0
	s_add_u32 s8, s62, 0x31ba4600
	s_addc_u32 s9, s63, 0
	s_add_u32 s10, s62, 0x31ba4700
	s_addc_u32 s11, s63, 0
	s_add_u32 s12, s62, 0x31ba4800
	s_addc_u32 s13, s63, 0
	s_add_u32 s14, s62, 0x31ba4900
	s_addc_u32 s15, s63, 0
	s_add_u32 s16, s62, 0x31ba4a00
	s_addc_u32 s17, s63, 0
	s_add_u32 s18, s62, 0x31ba4b00
	s_addc_u32 s19, s63, 0
	s_add_u32 s20, s62, 0x31ba4c00
	s_addc_u32 s21, s63, 0
	s_add_u32 s22, s62, 0x31ba4d00
	s_addc_u32 s23, s63, 0
	s_add_u32 s24, s62, 0x31ba4e00
	s_addc_u32 s25, s63, 0
	s_add_u32 s26, s62, 0x31ba4f00
	s_addc_u32 s27, s63, 0
	s_add_u32 s28, s62, 0x31ba5000
	s_addc_u32 s29, s63, 0
	s_add_u32 s30, s62, 0x31ba5100
	s_addc_u32 s31, s63, 0
	s_add_u32 s34, s62, 0x31ba5200
	s_addc_u32 s35, s63, 0
	s_mul_i32 s33, s65, s59
	s_add_u32 s36, s62, 0x31ba5300
	s_mul_i32 s33, s33, s64
	s_addc_u32 s37, s63, 0
	s_mov_b32 s40, 1
	v_mov_b32_e32 v16, 0
	s_branch .LBB0_1112
